# GEMM K-loop back-edge rotation: counter, pointer advance, next-tile select and exit test moved from after the loop-back barrier to the end of the last load segment; barrier is the loop head; plus phas
# baseline (speedup 1.0000x reference)
; #define PG8_STAGE(bufoff, gbase, voff) do { _Pragma("unroll") for (int _i = 0; _i < 2; ++_i) \
;         __builtin_amdgcn_global_load_lds((const unsigned*)((const char*)(gbase) + (voff)[_i]), (LAS unsigned*)(lds + (bufoff) + ldsw + _i * 8192), 16, 0, 0); } while (0)
; #define PG8_LDA(dst, b, h) do { _Pragma("unroll") for (int m = 0; m < 4; ++m) _Pragma("unroll") for (int k = 0; k < 2; ++k) dst[m][k] = *(const LAS bf16x8*)(lds + PG8_SA(b, h) + aoff + m * 2048 + k * 1024); } while (0)
; #define PG8_LDB(dst, b, h) do { _Pragma("unroll") for (int n = 0; n < 2; ++n) _Pragma("unroll") for (int k = 0; k < 2; ++k) dst[n][k] = *(const LAS bf16x8*)(lds + PG8_SB(b, h) + boff + n * 2048 + k * 1024); } while (0)
; #define PG8_SCHED __builtin_amdgcn_sched_barrier(0)
; __device__ __forceinline__ void gemm_phase(LAS unsigned char* lds, const GP p, const int tid) {
;     ...
;         for (int t = 0; t < nt; t += 2) {
;             const bool last = (t == nt - 2);
;             if (last && p.mode != 1) {
;                 const float* rp = p.rs + cur.pm * BM + wr * 64 + fr;
; #pragma unroll
;                 for (int ai = 0; ai < 2; ++ai)
; #pragma unroll
;                     for (int m = 0; m < 4; ++m) rsv[ai][m] = rp[ai * HALF + m * 16];
;             }
;             const char* a1 = cA + (size_t)(t + 1) * kstep;
;             const char* a2 = last ? nA : cA + (size_t)(t + 2) * kstep; const char* b2 = last ? nB : cB + (size_t)(t + 2) * kstep;
;             const char* a3 = a2 + kstep; const char* b3 = b2 + kstep;
;             PG8_LDB(B0, 0, 0); PG8_LDB(B1, 0, 1); PG8_SCHED; PG8_LDA(At, 0, 0); PG8_STAGE(PG8_SA(1, 1), a1 + hstep, voffA);
;     ...
; #pragma unroll
;         for (int a = 0; a < 2; ++a)
; #pragma unroll
;             for (int b = 0; b < 2; ++b)
; #pragma unroll
;                 for (int m = 0; m < 4; ++m)
; #pragma unroll
;                     for (int n = 0; n < 2; ++n) acc[a][b][m][n] = (f32x4){0.f, 0.f, 0.f, 0.f};
.LBB0_103:
	s_lshl_b32 s42, s80, 8
	s_ashr_i32 s43, s42, 31
	s_add_u32 s82, s82, 0x80
	s_addc_u32 s83, s83, 0
	s_add_u32 s81, s84, 0x100
	v_mov_b32_e32 v0, 0
	s_addc_u32 s91, s85, 0
	s_mov_b32 s98, 0
	v_mov_b32_e32 v1, v0
	v_mov_b32_e32 v2, v0
	v_mov_b32_e32 v3, v0
	v_mov_b32_e32 v4, v0
	v_mov_b32_e32 v5, v0
	v_mov_b32_e32 v6, v0
	v_mov_b32_e32 v7, v0
	v_mov_b32_e32 v16, v0
	v_mov_b32_e32 v17, v0
	v_mov_b32_e32 v18, v0
	v_mov_b32_e32 v19, v0
	v_mov_b32_e32 v20, v0
	v_mov_b32_e32 v21, v0
	v_mov_b32_e32 v22, v0
	v_mov_b32_e32 v23, v0
	v_mov_b32_e32 v32, v0
	v_mov_b32_e32 v33, v0
	v_mov_b32_e32 v34, v0
	v_mov_b32_e32 v35, v0
	v_mov_b32_e32 v36, v0
	v_mov_b32_e32 v37, v0
	v_mov_b32_e32 v38, v0
	v_mov_b32_e32 v39, v0
	v_mov_b32_e32 v48, v0
	v_mov_b32_e32 v49, v0
	v_mov_b32_e32 v50, v0
	v_mov_b32_e32 v51, v0
	v_mov_b32_e32 v52, v0
	v_mov_b32_e32 v53, v0
	v_mov_b32_e32 v54, v0
	v_mov_b32_e32 v55, v0
	v_mov_b32_e32 v8, v0
	v_mov_b32_e32 v9, v0
	v_mov_b32_e32 v10, v0
	v_mov_b32_e32 v11, v0
	v_mov_b32_e32 v12, v0
	v_mov_b32_e32 v13, v0
	v_mov_b32_e32 v14, v0
	v_mov_b32_e32 v15, v0
	v_mov_b32_e32 v24, v0
	v_mov_b32_e32 v25, v0
	v_mov_b32_e32 v26, v0
	v_mov_b32_e32 v27, v0
	v_mov_b32_e32 v28, v0
	v_mov_b32_e32 v29, v0
	v_mov_b32_e32 v30, v0
	v_mov_b32_e32 v31, v0
	v_mov_b32_e32 v40, v0
	v_mov_b32_e32 v41, v0
	v_mov_b32_e32 v42, v0
	v_mov_b32_e32 v43, v0
	v_mov_b32_e32 v44, v0
	v_mov_b32_e32 v45, v0
	v_mov_b32_e32 v46, v0
	v_mov_b32_e32 v47, v0
	v_mov_b32_e32 v56, v0
	v_mov_b32_e32 v57, v0
	v_mov_b32_e32 v58, v0
	v_mov_b32_e32 v59, v0
	v_mov_b32_e32 v60, v0
	v_mov_b32_e32 v61, v0
	v_mov_b32_e32 v62, v0
	v_mov_b32_e32 v63, v0
	v_mov_b32_e32 v64, v0
	v_mov_b32_e32 v65, v0
	v_mov_b32_e32 v66, v0
	v_mov_b32_e32 v67, v0
	v_mov_b32_e32 v68, v0
	v_mov_b32_e32 v69, v0
	v_mov_b32_e32 v70, v0
	v_mov_b32_e32 v71, v0
	v_mov_b32_e32 v80, v0
	v_mov_b32_e32 v81, v0
	v_mov_b32_e32 v82, v0
	v_mov_b32_e32 v83, v0
	v_mov_b32_e32 v84, v0
	v_mov_b32_e32 v85, v0
	v_mov_b32_e32 v86, v0
	v_mov_b32_e32 v87, v0
	v_mov_b32_e32 v96, v0
	v_mov_b32_e32 v97, v0
	v_mov_b32_e32 v98, v0
	v_mov_b32_e32 v99, v0
	v_mov_b32_e32 v100, v0
	v_mov_b32_e32 v101, v0
	v_mov_b32_e32 v102, v0
	v_mov_b32_e32 v103, v0
	v_mov_b32_e32 v112, v0
	v_mov_b32_e32 v113, v0
	v_mov_b32_e32 v114, v0
	v_mov_b32_e32 v115, v0
	v_mov_b32_e32 v116, v0
	v_mov_b32_e32 v117, v0
	v_mov_b32_e32 v118, v0
	v_mov_b32_e32 v119, v0
	v_mov_b32_e32 v72, v0
	v_mov_b32_e32 v73, v0
	v_mov_b32_e32 v74, v0
	v_mov_b32_e32 v75, v0
	v_mov_b32_e32 v76, v0
	v_mov_b32_e32 v77, v0
	v_mov_b32_e32 v78, v0
	v_mov_b32_e32 v79, v0
	v_mov_b32_e32 v88, v0
	v_mov_b32_e32 v89, v0
	v_mov_b32_e32 v90, v0
	v_mov_b32_e32 v91, v0
	v_mov_b32_e32 v92, v0
	v_mov_b32_e32 v93, v0
	v_mov_b32_e32 v94, v0
	v_mov_b32_e32 v95, v0
	v_mov_b32_e32 v104, v0
	v_mov_b32_e32 v105, v0
	v_mov_b32_e32 v106, v0
	v_mov_b32_e32 v107, v0
	v_mov_b32_e32 v108, v0
	v_mov_b32_e32 v109, v0
	v_mov_b32_e32 v110, v0
	v_mov_b32_e32 v111, v0
	v_mov_b32_e32 v120, v0
	v_mov_b32_e32 v121, v0
	v_mov_b32_e32 v122, v0
	v_mov_b32_e32 v123, v0
	v_mov_b32_e32 v124, v0
	v_mov_b32_e32 v125, v0
	v_mov_b32_e32 v126, v0
	v_mov_b32_e32 v127, v0
	v_lshl_add_u64 v[128:129], s[42:43], 2, v[154:155]
	s_cmp_eq_u32 s59, s98
	s_cselect_b64 s[84:85], -1, 0
	s_and_b64 vcc, s[22:23], s[84:85]
	s_add_i32 s98, s98, 2
	s_add_u32 s43, s82, 0x80
	s_addc_u32 s99, s83, 0
	s_and_b64 s[86:87], s[84:85], exec
	s_cselect_b32 s87, s77, s99
	s_cselect_b32 s86, s76, s43
	s_cselect_b32 s85, s79, s91
	s_cselect_b32 s84, s78, s81
	s_mov_b32 s43, 0x10000
	s_mov_b32 s99, 0x14000
	s_branch .Lk_top
.Lk_rs:
	global_load_dword v164, v[128:129], off
	global_load_dword v166, v[128:129], off offset:64
	global_load_dword v168, v[128:129], off offset:128
	global_load_dword v170, v[128:129], off offset:192
	global_load_dword v172, v[128:129], off offset:512
	global_load_dword v174, v[128:129], off offset:576
	global_load_dword v176, v[128:129], off offset:640
	global_load_dword v178, v[128:129], off offset:704
	s_branch .Lk_body
.LBB0_104:
	s_barrier
.Lk_top:
	s_cbranch_vccnz .Lk_rs
.Lk_body:
	v_add_u32_e32 v142, s43, v165
	ds_read_b128 v[130:133], v142
	ds_read_b128 v[134:137], v142 offset:1024
	ds_read_b128 v[138:141], v142 offset:2048
	ds_read_b128 v[180:183], v142 offset:3072
	v_add_u32_e32 v142, s99, v165
	ds_read_b128 v[184:187], v142
	ds_read_b128 v[188:191], v142 offset:1024
	ds_read_b128 v[192:195], v142 offset:2048
	ds_read_b128 v[196:199], v142 offset:3072
	v_lshl_add_u64 v[142:143], s[82:83], 0, v[160:161]
	s_add_i32 m0, s53, 0xc000
	ds_read_b128 v[200:203], v167
	ds_read_b128 v[204:207], v167 offset:1024
	ds_read_b128 v[208:211], v167 offset:2048
	ds_read_b128 v[218:221], v167 offset:3072
	ds_read_b128 v[222:225], v167 offset:4096
	ds_read_b128 v[226:229], v167 offset:5120
	ds_read_b128 v[230:233], v167 offset:6144
	ds_read_b128 v[234:237], v167 offset:7168
	global_load_lds_dwordx4 v[142:143], off
	v_lshl_add_u64 v[142:143], s[82:83], 0, v[162:163]
	s_add_i32 m0, s53, 0xe000
	s_nop 0
	global_load_lds_dwordx4 v[142:143], off
	s_waitcnt vmcnt(8)
	s_waitcnt lgkmcnt(0)
	s_barrier
; #define PG8_STAGE(bufoff, gbase, voff) do { _Pragma("unroll") for (int _i = 0; _i < 2; ++_i) \
;         __builtin_amdgcn_global_load_lds((const unsigned*)((const char*)(gbase) + (voff)[_i]), (LAS unsigned*)(lds + (bufoff) + ldsw + _i * 8192), 16, 0, 0); } while (0)
; #define PG8_LDA(dst, b, h) do { _Pragma("unroll") for (int m = 0; m < 4; ++m) _Pragma("unroll") for (int k = 0; k < 2; ++k) dst[m][k] = *(const LAS bf16x8*)(lds + PG8_SA(b, h) + aoff + m * 2048 + k * 1024); } while (0)
; #define PG8_MMA(ai, bj, At, Bt) do { __builtin_amdgcn_s_setprio(1); _Pragma("unroll") for (int m = 0; m < 4; ++m) _Pragma("unroll") for (int n = 0; n < 2; ++n) _Pragma("unroll") for (int k = 0; k < 2; ++k) \
;         acc[ai][bj][m][n] = __builtin_amdgcn_mfma_f32_16x16x32_bf16(Bt[n][k], At[m][k], acc[ai][bj][m][n], 0, 0, 0); __builtin_amdgcn_s_setprio(0); } while (0)
; #define PG8_WAIT_V(n) asm volatile("s_waitcnt vmcnt(" #n ")" ::: "memory")
; #define PG8_WAIT_L(n) asm volatile("s_waitcnt lgkmcnt(" #n ")" ::: "memory")
; #define PG8_BAR __builtin_amdgcn_s_barrier()
; #define PG8_SCHED __builtin_amdgcn_sched_barrier(0)
; __device__ __forceinline__ void gemm_phase(LAS unsigned char* lds, const GP p, const int tid) {
;     ...
;             PG8_WAIT_V(8); PG8_WAIT_L(0); PG8_BAR; PG8_MMA(0, 0, At, B0); PG8_MMA(0, 1, At, B1); PG8_BAR; PG8_SCHED;
;             PG8_LDA(At, 0, 1); PG8_STAGE(PG8_SB(0, 0), b2, voffB); PG8_STAGE(PG8_SB(0, 1), b2 + hstep, voffB); PG8_STAGE(PG8_SA(0, 0), a2, voffA);
;             PG8_WAIT_V(8); PG8_WAIT_L(0); PG8_BAR; PG8_MMA(1, 0, At, B0); PG8_MMA(1, 1, At, B1); PG8_BAR; PG8_SCHED;
	s_setprio 1
	s_waitcnt lgkmcnt(0)
	v_mfma_f32_16x16x32_bf16 v[124:127], v[130:133], v[200:203], v[124:127]
	v_mfma_f32_16x16x32_bf16 v[120:123], v[138:141], v[200:203], v[120:123]
	v_mfma_f32_16x16x32_bf16 v[108:111], v[130:133], v[208:211], v[108:111]
	v_mfma_f32_16x16x32_bf16 v[104:107], v[138:141], v[208:211], v[104:107]
	v_mfma_f32_16x16x32_bf16 v[92:95], v[130:133], v[222:225], v[92:95]
	v_mfma_f32_16x16x32_bf16 v[88:91], v[138:141], v[222:225], v[88:91]
	v_mfma_f32_16x16x32_bf16 v[76:79], v[130:133], v[230:233], v[76:79]
	v_mfma_f32_16x16x32_bf16 v[72:75], v[138:141], v[230:233], v[72:75]
	v_mfma_f32_16x16x32_bf16 v[124:127], v[134:137], v[204:207], v[124:127]
	v_mfma_f32_16x16x32_bf16 v[120:123], v[180:183], v[204:207], v[120:123]
	v_mfma_f32_16x16x32_bf16 v[108:111], v[134:137], v[218:221], v[108:111]
	v_mfma_f32_16x16x32_bf16 v[104:107], v[180:183], v[218:221], v[104:107]
	v_mfma_f32_16x16x32_bf16 v[92:95], v[134:137], v[226:229], v[92:95]
	v_mfma_f32_16x16x32_bf16 v[88:91], v[180:183], v[226:229], v[88:91]
	v_mfma_f32_16x16x32_bf16 v[76:79], v[134:137], v[234:237], v[76:79]
	v_mfma_f32_16x16x32_bf16 v[72:75], v[180:183], v[234:237], v[72:75]
	s_setprio 0
	s_setprio 1
	v_mfma_f32_16x16x32_bf16 v[116:119], v[184:187], v[200:203], v[116:119]
	v_mfma_f32_16x16x32_bf16 v[112:115], v[192:195], v[200:203], v[112:115]
	v_mfma_f32_16x16x32_bf16 v[100:103], v[184:187], v[208:211], v[100:103]
	v_mfma_f32_16x16x32_bf16 v[96:99], v[192:195], v[208:211], v[96:99]
	v_mfma_f32_16x16x32_bf16 v[84:87], v[184:187], v[222:225], v[84:87]
	v_mfma_f32_16x16x32_bf16 v[80:83], v[192:195], v[222:225], v[80:83]
	v_mfma_f32_16x16x32_bf16 v[68:71], v[184:187], v[230:233], v[68:71]
	v_mfma_f32_16x16x32_bf16 v[64:67], v[192:195], v[230:233], v[64:67]
	v_mfma_f32_16x16x32_bf16 v[116:119], v[188:191], v[204:207], v[116:119]
	v_mfma_f32_16x16x32_bf16 v[112:115], v[196:199], v[204:207], v[112:115]
	v_mfma_f32_16x16x32_bf16 v[100:103], v[188:191], v[218:221], v[100:103]
	v_mfma_f32_16x16x32_bf16 v[96:99], v[196:199], v[218:221], v[96:99]
	v_mfma_f32_16x16x32_bf16 v[84:87], v[188:191], v[226:229], v[84:87]
	v_mfma_f32_16x16x32_bf16 v[80:83], v[196:199], v[226:229], v[80:83]
	v_mfma_f32_16x16x32_bf16 v[68:71], v[188:191], v[234:237], v[68:71]
	v_mfma_f32_16x16x32_bf16 v[64:67], v[196:199], v[234:237], v[64:67]
	s_setprio 0
	s_barrier
	s_add_i32 s43, s43, s52
	v_lshl_add_u64 v[142:143], s[84:85], 0, v[148:149]
	s_mov_b32 m0, s43
	ds_read_b128 v[200:203], v167 offset:16384
	ds_read_b128 v[204:207], v167 offset:17408
	ds_read_b128 v[208:211], v167 offset:18432
	ds_read_b128 v[218:221], v167 offset:19456
	ds_read_b128 v[222:225], v167 offset:20480
	ds_read_b128 v[226:229], v167 offset:21504
	ds_read_b128 v[230:233], v167 offset:22528
	ds_read_b128 v[234:237], v167 offset:23552
	global_load_lds_dwordx4 v[142:143], off
	s_add_i32 m0, s43, 0x2000
	v_lshl_add_u64 v[238:239], s[84:85], 0, v[152:153]
	s_add_u32 s84, s84, s74
	s_addc_u32 s85, s85, 0
	s_add_i32 s43, s99, s52
	global_load_lds_dwordx4 v[238:239], off
	v_lshl_add_u64 v[240:241], s[84:85], 0, v[148:149]
	s_mov_b32 m0, s43
	v_lshl_add_u64 v[242:243], s[84:85], 0, v[152:153]
	global_load_lds_dwordx4 v[240:241], off
	s_add_i32 m0, s43, 0x2000
	v_lshl_add_u64 v[244:245], s[86:87], 0, v[146:147]
	global_load_lds_dwordx4 v[242:243], off
	s_mov_b32 m0, s53
	v_lshl_add_u64 v[246:247], s[86:87], 0, v[150:151]
	global_load_lds_dwordx4 v[244:245], off
	s_mov_b32 m0, s54
	s_nop 0
	global_load_lds_dwordx4 v[246:247], off
	s_waitcnt vmcnt(8)
	s_waitcnt lgkmcnt(0)
	s_barrier
	s_setprio 1
	s_waitcnt lgkmcnt(0)
	v_mfma_f32_16x16x32_bf16 v[60:63], v[130:133], v[200:203], v[60:63]
	v_mfma_f32_16x16x32_bf16 v[56:59], v[138:141], v[200:203], v[56:59]
	v_mfma_f32_16x16x32_bf16 v[44:47], v[130:133], v[208:211], v[44:47]
	v_mfma_f32_16x16x32_bf16 v[40:43], v[138:141], v[208:211], v[40:43]
	v_mfma_f32_16x16x32_bf16 v[28:31], v[130:133], v[222:225], v[28:31]
	v_mfma_f32_16x16x32_bf16 v[24:27], v[138:141], v[222:225], v[24:27]
	v_mfma_f32_16x16x32_bf16 v[12:15], v[130:133], v[230:233], v[12:15]
	v_mfma_f32_16x16x32_bf16 v[8:11], v[138:141], v[230:233], v[8:11]
	v_mfma_f32_16x16x32_bf16 v[60:63], v[134:137], v[204:207], v[60:63]
	v_mfma_f32_16x16x32_bf16 v[56:59], v[180:183], v[204:207], v[56:59]
	v_mfma_f32_16x16x32_bf16 v[44:47], v[134:137], v[218:221], v[44:47]
	v_mfma_f32_16x16x32_bf16 v[40:43], v[180:183], v[218:221], v[40:43]
	v_mfma_f32_16x16x32_bf16 v[28:31], v[134:137], v[226:229], v[28:31]
	v_mfma_f32_16x16x32_bf16 v[24:27], v[180:183], v[226:229], v[24:27]
	v_mfma_f32_16x16x32_bf16 v[12:15], v[134:137], v[234:237], v[12:15]
	v_mfma_f32_16x16x32_bf16 v[8:11], v[180:183], v[234:237], v[8:11]
	s_setprio 0
	s_setprio 1
	v_mfma_f32_16x16x32_bf16 v[52:55], v[184:187], v[200:203], v[52:55]
	v_mfma_f32_16x16x32_bf16 v[48:51], v[192:195], v[200:203], v[48:51]
	v_mfma_f32_16x16x32_bf16 v[36:39], v[184:187], v[208:211], v[36:39]
	v_mfma_f32_16x16x32_bf16 v[32:35], v[192:195], v[208:211], v[32:35]
	v_mfma_f32_16x16x32_bf16 v[20:23], v[184:187], v[222:225], v[20:23]
	v_mfma_f32_16x16x32_bf16 v[16:19], v[192:195], v[222:225], v[16:19]
	v_mfma_f32_16x16x32_bf16 v[4:7], v[184:187], v[230:233], v[4:7]
	v_mfma_f32_16x16x32_bf16 v[0:3], v[192:195], v[230:233], v[0:3]
	v_mfma_f32_16x16x32_bf16 v[52:55], v[188:191], v[204:207], v[52:55]
	v_mfma_f32_16x16x32_bf16 v[48:51], v[196:199], v[204:207], v[48:51]
	v_mfma_f32_16x16x32_bf16 v[36:39], v[188:191], v[218:221], v[36:39]
	v_mfma_f32_16x16x32_bf16 v[32:35], v[196:199], v[218:221], v[32:35]
	v_mfma_f32_16x16x32_bf16 v[20:23], v[188:191], v[226:229], v[20:23]
	v_mfma_f32_16x16x32_bf16 v[16:19], v[196:199], v[226:229], v[16:19]
	v_mfma_f32_16x16x32_bf16 v[4:7], v[188:191], v[234:237], v[4:7]
	v_mfma_f32_16x16x32_bf16 v[0:3], v[196:199], v[234:237], v[0:3]
	s_setprio 0
	s_barrier
; #define PG8_STAGE(bufoff, gbase, voff) do { _Pragma("unroll") for (int _i = 0; _i < 2; ++_i) \
;         __builtin_amdgcn_global_load_lds((const unsigned*)((const char*)(gbase) + (voff)[_i]), (LAS unsigned*)(lds + (bufoff) + ldsw + _i * 8192), 16, 0, 0); } while (0)
; #define PG8_LDA(dst, b, h) do { _Pragma("unroll") for (int m = 0; m < 4; ++m) _Pragma("unroll") for (int k = 0; k < 2; ++k) dst[m][k] = *(const LAS bf16x8*)(lds + PG8_SA(b, h) + aoff + m * 2048 + k * 1024); } while (0)
; #define PG8_LDB(dst, b, h) do { _Pragma("unroll") for (int n = 0; n < 2; ++n) _Pragma("unroll") for (int k = 0; k < 2; ++k) dst[n][k] = *(const LAS bf16x8*)(lds + PG8_SB(b, h) + boff + n * 2048 + k * 1024); } while (0)
; #define PG8_MMA(ai, bj, At, Bt) do { __builtin_amdgcn_s_setprio(1); _Pragma("unroll") for (int m = 0; m < 4; ++m) _Pragma("unroll") for (int n = 0; n < 2; ++n) _Pragma("unroll") for (int k = 0; k < 2; ++k) \
;         acc[ai][bj][m][n] = __builtin_amdgcn_mfma_f32_16x16x32_bf16(Bt[n][k], At[m][k], acc[ai][bj][m][n], 0, 0, 0); __builtin_amdgcn_s_setprio(0); } while (0)
; #define PG8_WAIT_V(n) asm volatile("s_waitcnt vmcnt(" #n ")" ::: "memory")
; #define PG8_WAIT_L(n) asm volatile("s_waitcnt lgkmcnt(" #n ")" ::: "memory")
; #define PG8_BAR __builtin_amdgcn_s_barrier()
; #define PG8_SCHED __builtin_amdgcn_sched_barrier(0)
; __device__ __forceinline__ void gemm_phase(LAS unsigned char* lds, const GP p, const int tid) {
;     ...
;             PG8_LDB(B0, 1, 0); PG8_LDB(B1, 1, 1); PG8_SCHED; PG8_LDA(At, 1, 0); PG8_STAGE(PG8_SA(0, 1), a2 + hstep, voffA);
;             PG8_WAIT_V(8); PG8_WAIT_L(0); PG8_BAR; PG8_MMA(0, 0, At, B0); PG8_MMA(0, 1, At, B1); PG8_BAR; PG8_SCHED;
	s_add_i32 s43, 0, 0x18000
	v_add_u32_e32 v144, s43, v165
	s_add_i32 s99, 0, 0x1c000
	ds_read_b128 v[130:133], v144
	ds_read_b128 v[134:137], v144 offset:1024
	ds_read_b128 v[138:141], v144 offset:2048
	ds_read_b128 v[180:183], v144 offset:3072
	v_add_u32_e32 v144, s99, v165
	ds_read_b128 v[184:187], v144
	ds_read_b128 v[188:191], v144 offset:1024
	ds_read_b128 v[192:195], v144 offset:2048
	ds_read_b128 v[196:199], v144 offset:3072
	s_add_u32 s84, s86, s74
	s_addc_u32 s85, s87, 0
	s_mov_b32 m0, s55
	v_lshl_add_u64 v[248:249], s[84:85], 0, v[146:147]
	ds_read_b128 v[200:203], v167 offset:32768
	ds_read_b128 v[204:207], v167 offset:33792
	ds_read_b128 v[208:211], v167 offset:34816
	ds_read_b128 v[218:221], v167 offset:35840
	ds_read_b128 v[222:225], v167 offset:36864
	ds_read_b128 v[226:229], v167 offset:37888
	ds_read_b128 v[230:233], v167 offset:38912
	ds_read_b128 v[234:237], v167 offset:39936
	global_load_lds_dwordx4 v[248:249], off
	v_lshl_add_u64 v[248:249], s[84:85], 0, v[150:151]
	s_mov_b32 m0, s56
	s_nop 0
	global_load_lds_dwordx4 v[248:249], off
	s_waitcnt vmcnt(8)
	s_waitcnt lgkmcnt(0)
	s_barrier
	s_setprio 1
	s_waitcnt lgkmcnt(0)
	v_mfma_f32_16x16x32_bf16 v[124:127], v[130:133], v[200:203], v[124:127]
	v_mfma_f32_16x16x32_bf16 v[120:123], v[138:141], v[200:203], v[120:123]
	v_mfma_f32_16x16x32_bf16 v[108:111], v[130:133], v[208:211], v[108:111]
	v_mfma_f32_16x16x32_bf16 v[104:107], v[138:141], v[208:211], v[104:107]
	v_mfma_f32_16x16x32_bf16 v[92:95], v[130:133], v[222:225], v[92:95]
	v_mfma_f32_16x16x32_bf16 v[88:91], v[138:141], v[222:225], v[88:91]
	v_mfma_f32_16x16x32_bf16 v[76:79], v[130:133], v[230:233], v[76:79]
	v_mfma_f32_16x16x32_bf16 v[72:75], v[138:141], v[230:233], v[72:75]
	v_mfma_f32_16x16x32_bf16 v[124:127], v[134:137], v[204:207], v[124:127]
	v_mfma_f32_16x16x32_bf16 v[120:123], v[180:183], v[204:207], v[120:123]
	v_mfma_f32_16x16x32_bf16 v[108:111], v[134:137], v[218:221], v[108:111]
	v_mfma_f32_16x16x32_bf16 v[104:107], v[180:183], v[218:221], v[104:107]
	v_mfma_f32_16x16x32_bf16 v[92:95], v[134:137], v[226:229], v[92:95]
	v_mfma_f32_16x16x32_bf16 v[88:91], v[180:183], v[226:229], v[88:91]
	v_mfma_f32_16x16x32_bf16 v[76:79], v[134:137], v[234:237], v[76:79]
	v_mfma_f32_16x16x32_bf16 v[72:75], v[180:183], v[234:237], v[72:75]
	s_setprio 0
	s_setprio 1
	v_mfma_f32_16x16x32_bf16 v[116:119], v[184:187], v[200:203], v[116:119]
	v_mfma_f32_16x16x32_bf16 v[112:115], v[192:195], v[200:203], v[112:115]
	v_mfma_f32_16x16x32_bf16 v[100:103], v[184:187], v[208:211], v[100:103]
	v_mfma_f32_16x16x32_bf16 v[96:99], v[192:195], v[208:211], v[96:99]
	v_mfma_f32_16x16x32_bf16 v[84:87], v[184:187], v[222:225], v[84:87]
	v_mfma_f32_16x16x32_bf16 v[80:83], v[192:195], v[222:225], v[80:83]
	v_mfma_f32_16x16x32_bf16 v[68:71], v[184:187], v[230:233], v[68:71]
	v_mfma_f32_16x16x32_bf16 v[64:67], v[192:195], v[230:233], v[64:67]
	v_mfma_f32_16x16x32_bf16 v[116:119], v[188:191], v[204:207], v[116:119]
	v_mfma_f32_16x16x32_bf16 v[112:115], v[196:199], v[204:207], v[112:115]
	v_mfma_f32_16x16x32_bf16 v[100:103], v[188:191], v[218:221], v[100:103]
	v_mfma_f32_16x16x32_bf16 v[96:99], v[196:199], v[218:221], v[96:99]
	v_mfma_f32_16x16x32_bf16 v[84:87], v[188:191], v[226:229], v[84:87]
	v_mfma_f32_16x16x32_bf16 v[80:83], v[196:199], v[226:229], v[80:83]
	v_mfma_f32_16x16x32_bf16 v[68:71], v[188:191], v[234:237], v[68:71]
	v_mfma_f32_16x16x32_bf16 v[64:67], v[196:199], v[234:237], v[64:67]
	s_setprio 0
	s_barrier
; #define PG8_STAGE(bufoff, gbase, voff) do { _Pragma("unroll") for (int _i = 0; _i < 2; ++_i) \
;         __builtin_amdgcn_global_load_lds((const unsigned*)((const char*)(gbase) + (voff)[_i]), (LAS unsigned*)(lds + (bufoff) + ldsw + _i * 8192), 16, 0, 0); } while (0)
; #define PG8_LDA(dst, b, h) do { _Pragma("unroll") for (int m = 0; m < 4; ++m) _Pragma("unroll") for (int k = 0; k < 2; ++k) dst[m][k] = *(const LAS bf16x8*)(lds + PG8_SA(b, h) + aoff + m * 2048 + k * 1024); } while (0)
; #define PG8_MMA(ai, bj, At, Bt) do { __builtin_amdgcn_s_setprio(1); _Pragma("unroll") for (int m = 0; m < 4; ++m) _Pragma("unroll") for (int n = 0; n < 2; ++n) _Pragma("unroll") for (int k = 0; k < 2; ++k) \
;         acc[ai][bj][m][n] = __builtin_amdgcn_mfma_f32_16x16x32_bf16(Bt[n][k], At[m][k], acc[ai][bj][m][n], 0, 0, 0); __builtin_amdgcn_s_setprio(0); } while (0)
; #define PG8_WAIT_V(n) asm volatile("s_waitcnt vmcnt(" #n ")" ::: "memory")
; #define PG8_WAIT_L(n) asm volatile("s_waitcnt lgkmcnt(" #n ")" ::: "memory")
; #define PG8_BAR __builtin_amdgcn_s_barrier()
; #define PG8_SCHED __builtin_amdgcn_sched_barrier(0)
; __device__ __forceinline__ void gemm_phase(LAS unsigned char* lds, const GP p, const int tid) {
;     ...
;         for (int t = 0; t < nt; t += 2) {
;             const bool last = (t == nt - 2);
;             if (last && p.mode != 1) {
;                 const float* rp = p.rs + cur.pm * BM + wr * 64 + fr;
; #pragma unroll
;                 for (int ai = 0; ai < 2; ++ai)
; #pragma unroll
;                     for (int m = 0; m < 4; ++m) rsv[ai][m] = rp[ai * HALF + m * 16];
;             }
;             const char* a1 = cA + (size_t)(t + 1) * kstep;
;             const char* a2 = last ? nA : cA + (size_t)(t + 2) * kstep; const char* b2 = last ? nB : cB + (size_t)(t + 2) * kstep;
;             const char* a3 = a2 + kstep; const char* b3 = b2 + kstep;
;     ...
;             PG8_LDA(At, 1, 1); PG8_STAGE(PG8_SB(1, 0), b3, voffB); PG8_STAGE(PG8_SB(1, 1), b3 + hstep, voffB); PG8_STAGE(PG8_SA(1, 0), a3, voffA);
;             PG8_WAIT_V(8); PG8_WAIT_L(0); PG8_BAR; PG8_MMA(1, 0, At, B0); PG8_MMA(1, 1, At, B1); PG8_BAR; PG8_SCHED;
	s_add_i32 s43, s43, s52
	v_lshl_add_u64 v[142:143], v[142:143], 0, s[36:37]
	s_mov_b32 m0, s43
	ds_read_b128 v[200:203], v167 offset:49152
	ds_read_b128 v[204:207], v167 offset:50176
	ds_read_b128 v[208:211], v167 offset:51200
	ds_read_b128 v[218:221], v167 offset:52224
	ds_read_b128 v[222:225], v167 offset:53248
	ds_read_b128 v[226:229], v167 offset:54272
	ds_read_b128 v[230:233], v167 offset:55296
	ds_read_b128 v[234:237], v167 offset:56320
	global_load_lds_dwordx4 v[142:143], off
	v_lshl_add_u64 v[142:143], v[238:239], 0, s[36:37]
	s_add_i32 m0, s43, 0x2000
	s_add_i32 s43, s99, s52
	global_load_lds_dwordx4 v[142:143], off
	v_lshl_add_u64 v[142:143], v[240:241], 0, s[36:37]
	s_mov_b32 m0, s43
	s_nop 0
	global_load_lds_dwordx4 v[142:143], off
	v_lshl_add_u64 v[142:143], v[242:243], 0, s[36:37]
	s_add_i32 m0, s43, 0x2000
	s_nop 0
	global_load_lds_dwordx4 v[142:143], off
	v_lshl_add_u64 v[142:143], v[244:245], 0, s[36:37]
	s_mov_b32 m0, s57
	s_nop 0
	global_load_lds_dwordx4 v[142:143], off
	v_lshl_add_u64 v[142:143], v[246:247], 0, s[36:37]
	s_mov_b32 m0, s58
	s_nop 0
	global_load_lds_dwordx4 v[142:143], off
	s_cmp_eq_u32 s59, s98
	s_cselect_b64 s[84:85], -1, 0
	s_and_b64 vcc, s[22:23], s[84:85]
	s_add_i32 s98, s98, 2
	s_add_u32 s82, s82, 0x100
	s_addc_u32 s83, s83, 0
	s_add_u32 s81, s81, 0x100
	s_addc_u32 s91, s91, 0
	s_add_u32 s43, s82, 0x80
	s_addc_u32 s99, s83, 0
	s_and_b64 s[86:87], s[84:85], exec
	s_cselect_b32 s87, s77, s99
	s_cselect_b32 s86, s76, s43
	s_cselect_b32 s85, s79, s91
	s_cselect_b32 s84, s78, s81
	s_mov_b32 s43, 0x10000
	s_mov_b32 s99, 0x14000
	s_cmp_gt_u32 s98, s60
	s_waitcnt vmcnt(8)
	s_waitcnt lgkmcnt(0)
	s_barrier
	s_setprio 1
	s_waitcnt lgkmcnt(0)
	v_mfma_f32_16x16x32_bf16 v[60:63], v[130:133], v[200:203], v[60:63]
	v_mfma_f32_16x16x32_bf16 v[56:59], v[138:141], v[200:203], v[56:59]
	v_mfma_f32_16x16x32_bf16 v[44:47], v[130:133], v[208:211], v[44:47]
	v_mfma_f32_16x16x32_bf16 v[40:43], v[138:141], v[208:211], v[40:43]
	v_mfma_f32_16x16x32_bf16 v[28:31], v[130:133], v[222:225], v[28:31]
	v_mfma_f32_16x16x32_bf16 v[24:27], v[138:141], v[222:225], v[24:27]
	v_mfma_f32_16x16x32_bf16 v[12:15], v[130:133], v[230:233], v[12:15]
	v_mfma_f32_16x16x32_bf16 v[8:11], v[138:141], v[230:233], v[8:11]
	v_mfma_f32_16x16x32_bf16 v[60:63], v[134:137], v[204:207], v[60:63]
	v_mfma_f32_16x16x32_bf16 v[56:59], v[180:183], v[204:207], v[56:59]
	v_mfma_f32_16x16x32_bf16 v[44:47], v[134:137], v[218:221], v[44:47]
	v_mfma_f32_16x16x32_bf16 v[40:43], v[180:183], v[218:221], v[40:43]
	v_mfma_f32_16x16x32_bf16 v[28:31], v[134:137], v[226:229], v[28:31]
	v_mfma_f32_16x16x32_bf16 v[24:27], v[180:183], v[226:229], v[24:27]
	v_mfma_f32_16x16x32_bf16 v[12:15], v[134:137], v[234:237], v[12:15]
	v_mfma_f32_16x16x32_bf16 v[8:11], v[180:183], v[234:237], v[8:11]
	s_setprio 0
	s_setprio 1
	v_mfma_f32_16x16x32_bf16 v[52:55], v[184:187], v[200:203], v[52:55]
	v_mfma_f32_16x16x32_bf16 v[48:51], v[192:195], v[200:203], v[48:51]
	v_mfma_f32_16x16x32_bf16 v[36:39], v[184:187], v[208:211], v[36:39]
	v_mfma_f32_16x16x32_bf16 v[32:35], v[192:195], v[208:211], v[32:35]
	v_mfma_f32_16x16x32_bf16 v[20:23], v[184:187], v[222:225], v[20:23]
	v_mfma_f32_16x16x32_bf16 v[16:19], v[192:195], v[222:225], v[16:19]
	v_mfma_f32_16x16x32_bf16 v[4:7], v[184:187], v[230:233], v[4:7]
	v_mfma_f32_16x16x32_bf16 v[0:3], v[192:195], v[230:233], v[0:3]
	v_mfma_f32_16x16x32_bf16 v[52:55], v[188:191], v[204:207], v[52:55]
	v_mfma_f32_16x16x32_bf16 v[48:51], v[196:199], v[204:207], v[48:51]
	v_mfma_f32_16x16x32_bf16 v[36:39], v[188:191], v[218:221], v[36:39]
	v_mfma_f32_16x16x32_bf16 v[32:35], v[196:199], v[218:221], v[32:35]
	v_mfma_f32_16x16x32_bf16 v[20:23], v[188:191], v[226:229], v[20:23]
	v_mfma_f32_16x16x32_bf16 v[16:19], v[196:199], v[226:229], v[16:19]
	v_mfma_f32_16x16x32_bf16 v[4:7], v[188:191], v[234:237], v[4:7]
	v_mfma_f32_16x16x32_bf16 v[0:3], v[196:199], v[234:237], v[0:3]
	s_setprio 0
	s_cbranch_scc0 .LBB0_104
	s_barrier
